# P5: ~12 us s_sleep before the sample-row out-projection task = larger XCD-class shift of the panel-GEMM unit boundaries (fused epilogue bursts under other classes' K-loops), on top of v73
# baseline (speedup 1.0000x reference)
; template <int RT, class F>
; __device__ __forceinline__ void sample_gemm_task(const bf16* A, const bf16* Bt, int K, int ct, int row0, int lane, F f) {
;     const int l15 = lane & 15, q4 = lane >> 4;
;     f32x4 acc[RT];
; #pragma unroll
;     for (int rt = 0; rt < RT; ++rt) acc[rt] = (f32x4){0.f, 0.f, 0.f, 0.f};
;     const bf16* bp = Bt + (size_t)(16 * ct + l15) * K + 8 * q4;
;     const bf16* ap = A + (size_t)(row0 + l15) * K + 8 * q4;
; __global__ void __launch_bounds__(NWAVES * 64, 2) fwd_kernel(Params P) {
;     ...
;             if (wave < 4) for (int tk = blockIdx.x; tk < 256; tk += G) {
;                 if (mask5 & 2) sample_gemm_task<1>((const bf16*)(ws + WS_MIX) + (size_t)MP * 1024, (const bf16*)(ws + WS_WOUT), 1024, tk & 63, 64 * (tk >> 6) + 16 * wave, lane, SEpiOut{P.x_s, (bf16*)(ws + WS_H1B)});
.LBB0_808:
	s_andn2_b64 vcc, exec, s[4:5]
	s_cbranch_vccnz .LBB0_812
	s_sleep 127
	s_sleep 127
	s_sleep 127
	s_lshl_b32 s9, s2, 11
	s_and_b32 s9, s9, 0x1f8000
	v_lshl_or_b32 v186, v226, 1, s9
	s_and_b32 s9, s8, 0xffffffc0
	v_add_u32_e32 v2, s9, v227
	v_ashrrev_i32_e32 v3, 31, v2
	v_lshlrev_b64 v[2:3], 11, v[2:3]
	s_waitcnt lgkmcnt(0)
	v_lshl_add_u64 v[8:9], v[190:191], 0, v[2:3]
	v_mov_b32_e32 v2, 0
	v_lshl_add_u64 v[6:7], v[190:191], 0, v[186:187]
	s_mov_b64 s[46:47], 0
	v_mov_b32_e32 v3, v2
	v_mov_b32_e32 v4, v2
	v_mov_b32_e32 v5, v2
